# v11 + StaticOrder unit header: division by the (always 8) group height replaced by shift/mask in the 7 unit loops
# baseline (speedup 1.0000x reference)
.LBB0_153:
	s_add_i32 s60, s60, 1
	s_mul_i32 s2, s60, s84
	s_mul_hi_u32 s3, s60, s72
	s_add_i32 s3, s3, s2
	s_mul_i32 s2, s60, s72
	v_readlane_b32 s11, v255, 5
	s_add_u32 s14, s2, s11
	s_addc_u32 s15, s3, s59
	v_cmp_gt_i64_e32 vcc, s[14:15], v[132:133]
	v_cmp_lt_i64_e64 s[2:3], s[14:15], v[130:131]
	s_cbranch_vccnz .LBB0_155
	s_ashr_i32 s10, s14, 31
	s_lshr_b32 s10, s10, 29
	s_add_i32 s10, s14, s10
	s_ashr_i32 s11, s10, 3
	s_and_b32 s10, s10, -8
	s_sub_i32 s10, s14, s10
	s_cmp_lt_i32 s10, 0
	s_cselect_b32 s12, s61, 0x2d6
	s_mul_i32 s10, s10, s12
	s_add_i32 s10, s10, s11
	s_mul_hi_i32 s11, s10, 0x2e8ba2e9
	s_lshr_b32 s12, s11, 31
	s_ashr_i32 s11, s11, 5
	s_add_i32 s11, s11, s12
	s_lshl_b32 s12, s11, 3
	s_mulk_i32 s11, 0xb0
	s_sub_i32 s11, s10, s11
	s_lshr_b32 s10, s11, 3
	s_and_b32 s11, s11, 7
	s_add_i32 s40, s12, s11

.LBB0_416:
	s_add_i32 s56, s56, 1
	s_mul_i32 s2, s56, s77
	s_mul_hi_u32 s3, s56, s72
	s_add_i32 s3, s3, s2
	s_mul_i32 s2, s56, s72
	v_readlane_b32 s4, v255, 5
	s_add_u32 s14, s2, s4
	s_addc_u32 s15, s3, s33
	v_cmp_gt_i64_e32 vcc, s[14:15], v[132:133]
	v_cmp_lt_i64_e64 s[4:5], s[14:15], v[130:131]
	s_cbranch_vccnz .LBB0_418
	s_ashr_i32 s2, s14, 31
	s_lshr_b32 s2, s2, 29
	s_add_i32 s2, s14, s2
	s_ashr_i32 s3, s2, 3
	s_and_b32 s2, s2, -8
	s_sub_i32 s2, s14, s2
	s_cmp_lt_i32 s2, 0
	s_cselect_b32 s12, s57, 0x108
	s_mul_i32 s2, s2, s12
	s_add_i32 s2, s2, s3
	s_ashr_i32 s3, s2, 31
	s_lshr_b32 s3, s3, 26
	s_add_i32 s3, s2, s3
	s_ashr_i32 s12, s3, 6
	s_lshl_b32 s12, s12, 3
	s_andn2_b32 s3, s3, 63
	s_sub_i32 s2, s2, s3
	s_lshr_b32 s26, s2, 3
	s_and_b32 s2, s2, 7
	s_add_i32 s36, s12, s2

.LBB0_554:
	s_add_i32 s54, s54, 1
	s_mul_i32 s2, s54, s75
	s_mul_hi_u32 s3, s54, s72
	s_add_i32 s3, s3, s2
	s_mul_i32 s2, s54, s72
	v_readlane_b32 s4, v255, 5
	s_add_u32 s14, s2, s4
	s_addc_u32 s15, s3, s33
	v_cmp_gt_i64_e32 vcc, s[14:15], v[132:133]
	v_cmp_lt_i64_e64 s[4:5], s[14:15], v[130:131]
	s_cbranch_vccnz .LBB0_556
	s_ashr_i32 s2, s14, 31
	s_lshr_b32 s2, s2, 29
	s_add_i32 s2, s14, s2
	s_ashr_i32 s3, s2, 3
	s_and_b32 s2, s2, -8
	s_sub_i32 s2, s14, s2
	s_cmp_lt_i32 s2, 0
	s_cselect_b32 s12, s55, 0x2d6
	s_mul_i32 s2, s2, s12
	s_add_i32 s2, s2, s3
	s_mul_hi_i32 s3, s2, 0x2e8ba2e9
	s_lshr_b32 s12, s3, 31
	s_ashr_i32 s3, s3, 5
	s_add_i32 s3, s3, s12
	s_lshl_b32 s12, s3, 3
	s_mulk_i32 s3, 0xb0
	s_sub_i32 s2, s2, s3
	s_lshr_b32 s24, s2, 3
	s_and_b32 s2, s2, 7
	s_add_i32 s26, s12, s2

.LBB0_749:
	s_add_i32 s57, s57, 1
	s_mul_i32 s2, s57, s40
	s_mul_hi_u32 s3, s57, s72
	s_add_i32 s3, s3, s2
	s_mul_i32 s2, s57, s72
	s_add_u32 s14, s2, s54
	s_addc_u32 s15, s3, s41
	v_cmp_gt_i64_e32 vcc, s[14:15], v[152:153]
	v_cmp_lt_i64_e64 s[4:5], s[14:15], v[150:151]
	s_cbranch_vccnz .LBB0_751
	s_ashr_i32 s2, s14, 31
	s_lshr_b32 s2, s2, 29
	s_add_i32 s2, s14, s2
	s_ashr_i32 s3, s2, 3
	s_and_b32 s2, s2, -8
	s_sub_i32 s2, s14, s2
	s_cmp_lt_i32 s2, 0
	s_movk_i32 s7, 0x109
	s_cselect_b32 s7, s7, 0x108
	s_mul_i32 s2, s2, s7
	s_add_i32 s2, s2, s3
	s_ashr_i32 s3, s2, 31
	s_lshr_b32 s3, s3, 26
	s_add_i32 s3, s2, s3
	s_ashr_i32 s7, s3, 6
	s_lshl_b32 s7, s7, 3
	s_andn2_b32 s3, s3, 63
	s_sub_i32 s2, s2, s3
	s_lshr_b32 s26, s2, 3
	s_and_b32 s2, s2, 7
	s_add_i32 s36, s7, s2

.LBB0_797:
	s_add_i32 s52, s52, 1
	s_mul_i32 s2, s52, s73
	s_mul_hi_u32 s3, s52, s72
	s_add_i32 s3, s3, s2
	s_mul_i32 s2, s52, s72
	v_readlane_b32 s4, v255, 5
	s_add_u32 s14, s2, s4
	s_addc_u32 s15, s3, s33
	v_cmp_gt_i64_e32 vcc, s[14:15], v[132:133]
	v_cmp_lt_i64_e64 s[4:5], s[14:15], v[130:131]
	s_cbranch_vccnz .LBB0_799
	s_ashr_i32 s2, s14, 31
	s_lshr_b32 s2, s2, 29
	s_add_i32 s2, s14, s2
	s_ashr_i32 s3, s2, 3
	s_and_b32 s2, s2, -8
	s_sub_i32 s2, s14, s2
	s_cmp_lt_i32 s2, 0
	s_cselect_b32 s10, s53, 0x2d6
	s_mul_i32 s2, s2, s10
	s_add_i32 s2, s2, s3
	s_mul_hi_i32 s3, s2, 0x2e8ba2e9
	s_lshr_b32 s10, s3, 31
	s_ashr_i32 s3, s3, 5
	s_add_i32 s3, s3, s10
	s_lshl_b32 s11, s3, 3
	s_mulk_i32 s3, 0xb0
	s_sub_i32 s2, s2, s3
	s_lshr_b32 s10, s2, 3
	s_and_b32 s2, s2, 7
	s_add_i32 s24, s11, s2

.LBB0_985:
	s_add_i32 s52, s52, 1
	s_mul_i32 s2, s52, s85
	s_mul_hi_u32 s3, s52, s72
	s_add_i32 s3, s3, s2
	s_mul_i32 s2, s52, s72
	v_readlane_b32 s11, v255, 5
	s_add_u32 s14, s2, s11
	s_addc_u32 s15, s3, s33
	v_cmp_gt_i64_e32 vcc, s[14:15], v[138:139]
	v_cmp_lt_i64_e64 s[2:3], s[14:15], v[136:137]
	s_cbranch_vccnz .LBB0_987
	s_ashr_i32 s10, s14, 31
	s_lshr_b32 s10, s10, 29
	s_add_i32 s10, s14, s10
	s_ashr_i32 s11, s10, 3
	s_and_b32 s10, s10, -8
	s_sub_i32 s10, s14, s10
	s_cmp_lt_i32 s10, 0
	s_cselect_b32 s12, s53, 0x84
	s_mul_i32 s10, s10, s12
	s_add_i32 s10, s10, s11
	s_ashr_i32 s11, s10, 31
	s_lshr_b32 s11, s11, 27
	s_add_i32 s11, s10, s11
	s_ashr_i32 s12, s11, 5
	s_lshl_b32 s12, s12, 3
	s_andn2_b32 s11, s11, 31
	s_sub_i32 s11, s10, s11
	s_lshr_b32 s10, s11, 3
	s_and_b32 s11, s11, 7
	s_add_i32 s24, s12, s11

.LBB0_1421:
	s_add_i32 s44, s44, 1
	s_mul_i32 s2, s44, s60
	s_mul_hi_u32 s3, s44, s72
	s_add_i32 s3, s3, s2
	s_mul_i32 s2, s44, s72
	v_readlane_b32 s11, v255, 5
	s_add_u32 s14, s2, s11
	s_addc_u32 s15, s3, s33
	v_cmp_gt_i64_e32 vcc, s[14:15], v[132:133]
	v_cmp_lt_i64_e64 s[2:3], s[14:15], v[130:131]
	s_cbranch_vccnz .LBB0_1423
	s_ashr_i32 s10, s14, 31
	s_lshr_b32 s10, s10, 29
	s_add_i32 s10, s14, s10
	s_ashr_i32 s11, s10, 3
	s_and_b32 s10, s10, -8
	s_sub_i32 s10, s14, s10
	s_cmp_lt_i32 s10, 0
	s_cselect_b32 s12, s45, 0x2d6
	s_mul_i32 s10, s10, s12
	s_add_i32 s10, s10, s11
	s_mul_hi_i32 s11, s10, 0x2e8ba2e9
	s_lshr_b32 s12, s11, 31
	s_ashr_i32 s11, s11, 5
	s_add_i32 s11, s11, s12
	s_lshl_b32 s12, s11, 3
	s_mulk_i32 s11, 0xb0
	s_sub_i32 s11, s10, s11
	s_lshr_b32 s10, s11, 3
	s_and_b32 s11, s11, 7
	s_add_i32 s20, s12, s11
